# ssd_pass_item (state scan after the attention item, both layers) hand-scheduled: all 66 loads issued up front with SGPR-base addressing, then the serial recurrence with counted waits
# speedup vs baseline: 1.0008x; 1.0008x over previous
.LBB0_673:
	s_and_b32 s4, s7, 0x700
	v_and_b32_e32 v0, 0xff, v164
	v_or_b32_e32 v0, s4, v0
	v_lshlrev_b32_e32 v0, 2, v0
	s_bfe_u32 s12, s9, 0x30003
	s_bfe_u32 s13, s9, 0x20006
	s_lshr_b32 s14, s9, 8
	s_lshl_b32 s15, s14, 2
	s_or_b32 s15, s15, s13
	s_mul_i32 s15, s15, 34
	s_lshl_b32 s4, s12, 13
	s_add_u32 s16, s0, s4
	s_addc_u32 s17, s1, 0
	s_lshl_b32 s4, s12, 2
	s_add_u32 s18, s2, s4
	s_addc_u32 s19, s6, 0
	s_cmp_eq_u32 s14, 0
	s_cselect_b32 s20, 0, 1
	s_cselect_b32 s21, 1, 0
	s_cselect_b32 s24, 2, 33
	s_cselect_b32 s25, 1, -1
	s_mov_b32 s5, s24
	v_mov_b32_e32 v2, 0
	v_mov_b32_e32 v3, 0
	s_waitcnt vmcnt(0)
	s_add_i32 s26, s15, s20
	s_lshl_b32 s27, s26, 5
	s_add_u32 s30, s18, s27
	s_addc_u32 s31, s19, 0
	s_lshl_b32 s27, s26, 16
	s_add_u32 s28, s16, s27
	s_addc_u32 s29, s17, 0
	global_load_dword v6, v1, s[30:31]
	global_load_dword v7, v0, s[28:29]
	s_add_i32 s26, s15, s21
	s_lshl_b32 s27, s26, 5
	s_add_u32 s30, s18, s27
	s_addc_u32 s31, s19, 0
	s_lshl_b32 s27, s26, 16
	s_add_u32 s28, s16, s27
	s_addc_u32 s29, s17, 0
	global_load_dword v8, v1, s[30:31]
	global_load_dword v9, v0, s[28:29]
	s_add_i32 s26, s15, s24
	s_add_i32 s24, s24, s25
	s_lshl_b32 s27, s26, 5
	s_add_u32 s30, s18, s27
	s_addc_u32 s31, s19, 0
	s_lshl_b32 s27, s26, 16
	s_add_u32 s28, s16, s27
	s_addc_u32 s29, s17, 0
	global_load_dword v10, v1, s[30:31]
	global_load_dword v11, v0, s[28:29]
	s_add_i32 s26, s15, s24
	s_add_i32 s24, s24, s25
	s_lshl_b32 s27, s26, 5
	s_add_u32 s30, s18, s27
	s_addc_u32 s31, s19, 0
	s_lshl_b32 s27, s26, 16
	s_add_u32 s28, s16, s27
	s_addc_u32 s29, s17, 0
	global_load_dword v12, v1, s[30:31]
	global_load_dword v13, v0, s[28:29]
	s_add_i32 s26, s15, s24
	s_add_i32 s24, s24, s25
	s_lshl_b32 s27, s26, 5
	s_add_u32 s30, s18, s27
	s_addc_u32 s31, s19, 0
	s_lshl_b32 s27, s26, 16
	s_add_u32 s28, s16, s27
	s_addc_u32 s29, s17, 0
	global_load_dword v14, v1, s[30:31]
	global_load_dword v15, v0, s[28:29]
	s_add_i32 s26, s15, s24
	s_add_i32 s24, s24, s25
	s_lshl_b32 s27, s26, 5
	s_add_u32 s30, s18, s27
	s_addc_u32 s31, s19, 0
	s_lshl_b32 s27, s26, 16
	s_add_u32 s28, s16, s27
	s_addc_u32 s29, s17, 0
	global_load_dword v16, v1, s[30:31]
	global_load_dword v17, v0, s[28:29]
	s_add_i32 s26, s15, s24
	s_add_i32 s24, s24, s25
	s_lshl_b32 s27, s26, 5
	s_add_u32 s30, s18, s27
	s_addc_u32 s31, s19, 0
	s_lshl_b32 s27, s26, 16
	s_add_u32 s28, s16, s27
	s_addc_u32 s29, s17, 0
	global_load_dword v18, v1, s[30:31]
	global_load_dword v19, v0, s[28:29]
	s_add_i32 s26, s15, s24
	s_add_i32 s24, s24, s25
	s_lshl_b32 s27, s26, 5
	s_add_u32 s30, s18, s27
	s_addc_u32 s31, s19, 0
	s_lshl_b32 s27, s26, 16
	s_add_u32 s28, s16, s27
	s_addc_u32 s29, s17, 0
	global_load_dword v20, v1, s[30:31]
	global_load_dword v21, v0, s[28:29]
	s_add_i32 s26, s15, s24
	s_add_i32 s24, s24, s25
	s_lshl_b32 s27, s26, 5
	s_add_u32 s30, s18, s27
	s_addc_u32 s31, s19, 0
	s_lshl_b32 s27, s26, 16
	s_add_u32 s28, s16, s27
	s_addc_u32 s29, s17, 0
	global_load_dword v22, v1, s[30:31]
	global_load_dword v23, v0, s[28:29]
	s_add_i32 s26, s15, s24
	s_add_i32 s24, s24, s25
	s_lshl_b32 s27, s26, 5
	s_add_u32 s30, s18, s27
	s_addc_u32 s31, s19, 0
	s_lshl_b32 s27, s26, 16
	s_add_u32 s28, s16, s27
	s_addc_u32 s29, s17, 0
	global_load_dword v24, v1, s[30:31]
	global_load_dword v25, v0, s[28:29]
	s_add_i32 s26, s15, s24
	s_add_i32 s24, s24, s25
	s_lshl_b32 s27, s26, 5
	s_add_u32 s30, s18, s27
	s_addc_u32 s31, s19, 0
	s_lshl_b32 s27, s26, 16
	s_add_u32 s28, s16, s27
	s_addc_u32 s29, s17, 0
	global_load_dword v26, v1, s[30:31]
	global_load_dword v27, v0, s[28:29]
	s_add_i32 s26, s15, s24
	s_add_i32 s24, s24, s25
	s_lshl_b32 s27, s26, 5
	s_add_u32 s30, s18, s27
	s_addc_u32 s31, s19, 0
	s_lshl_b32 s27, s26, 16
	s_add_u32 s28, s16, s27
	s_addc_u32 s29, s17, 0
	global_load_dword v28, v1, s[30:31]
	global_load_dword v29, v0, s[28:29]
	s_add_i32 s26, s15, s24
	s_add_i32 s24, s24, s25
	s_lshl_b32 s27, s26, 5
	s_add_u32 s30, s18, s27
	s_addc_u32 s31, s19, 0
	s_lshl_b32 s27, s26, 16
	s_add_u32 s28, s16, s27
	s_addc_u32 s29, s17, 0
	global_load_dword v30, v1, s[30:31]
	global_load_dword v31, v0, s[28:29]
	s_add_i32 s26, s15, s24
	s_add_i32 s24, s24, s25
	s_lshl_b32 s27, s26, 5
	s_add_u32 s30, s18, s27
	s_addc_u32 s31, s19, 0
	s_lshl_b32 s27, s26, 16
	s_add_u32 s28, s16, s27
	s_addc_u32 s29, s17, 0
	global_load_dword v32, v1, s[30:31]
	global_load_dword v33, v0, s[28:29]
	s_add_i32 s26, s15, s24
	s_add_i32 s24, s24, s25
	s_lshl_b32 s27, s26, 5
	s_add_u32 s30, s18, s27
	s_addc_u32 s31, s19, 0
	s_lshl_b32 s27, s26, 16
	s_add_u32 s28, s16, s27
	s_addc_u32 s29, s17, 0
	global_load_dword v34, v1, s[30:31]
	global_load_dword v35, v0, s[28:29]
	s_add_i32 s26, s15, s24
	s_add_i32 s24, s24, s25
	s_lshl_b32 s27, s26, 5
	s_add_u32 s30, s18, s27
	s_addc_u32 s31, s19, 0
	s_lshl_b32 s27, s26, 16
	s_add_u32 s28, s16, s27
	s_addc_u32 s29, s17, 0
	global_load_dword v36, v1, s[30:31]
	global_load_dword v37, v0, s[28:29]
	s_add_i32 s26, s15, s24
	s_add_i32 s24, s24, s25
	s_lshl_b32 s27, s26, 5
	s_add_u32 s30, s18, s27
	s_addc_u32 s31, s19, 0
	s_lshl_b32 s27, s26, 16
	s_add_u32 s28, s16, s27
	s_addc_u32 s29, s17, 0
	global_load_dword v38, v1, s[30:31]
	global_load_dword v39, v0, s[28:29]
	s_add_i32 s26, s15, s24
	s_add_i32 s24, s24, s25
	s_lshl_b32 s27, s26, 5
	s_add_u32 s30, s18, s27
	s_addc_u32 s31, s19, 0
	s_lshl_b32 s27, s26, 16
	s_add_u32 s28, s16, s27
	s_addc_u32 s29, s17, 0
	global_load_dword v40, v1, s[30:31]
	global_load_dword v41, v0, s[28:29]
	s_add_i32 s26, s15, s24
	s_add_i32 s24, s24, s25
	s_lshl_b32 s27, s26, 5
	s_add_u32 s30, s18, s27
	s_addc_u32 s31, s19, 0
	s_lshl_b32 s27, s26, 16
	s_add_u32 s28, s16, s27
	s_addc_u32 s29, s17, 0
	global_load_dword v42, v1, s[30:31]
	global_load_dword v43, v0, s[28:29]
	s_add_i32 s26, s15, s24
	s_add_i32 s24, s24, s25
	s_lshl_b32 s27, s26, 5
	s_add_u32 s30, s18, s27
	s_addc_u32 s31, s19, 0
	s_lshl_b32 s27, s26, 16
	s_add_u32 s28, s16, s27
	s_addc_u32 s29, s17, 0
	global_load_dword v44, v1, s[30:31]
	global_load_dword v45, v0, s[28:29]
	s_add_i32 s26, s15, s24
	s_add_i32 s24, s24, s25
	s_lshl_b32 s27, s26, 5
	s_add_u32 s30, s18, s27
	s_addc_u32 s31, s19, 0
	s_lshl_b32 s27, s26, 16
	s_add_u32 s28, s16, s27
	s_addc_u32 s29, s17, 0
	global_load_dword v46, v1, s[30:31]
	global_load_dword v47, v0, s[28:29]
	s_add_i32 s26, s15, s24
	s_add_i32 s24, s24, s25
	s_lshl_b32 s27, s26, 5
	s_add_u32 s30, s18, s27
	s_addc_u32 s31, s19, 0
	s_lshl_b32 s27, s26, 16
	s_add_u32 s28, s16, s27
	s_addc_u32 s29, s17, 0
	global_load_dword v48, v1, s[30:31]
	global_load_dword v49, v0, s[28:29]
	s_add_i32 s26, s15, s24
	s_add_i32 s24, s24, s25
	s_lshl_b32 s27, s26, 5
	s_add_u32 s30, s18, s27
	s_addc_u32 s31, s19, 0
	s_lshl_b32 s27, s26, 16
	s_add_u32 s28, s16, s27
	s_addc_u32 s29, s17, 0
	global_load_dword v50, v1, s[30:31]
	global_load_dword v51, v0, s[28:29]
	s_add_i32 s26, s15, s24
	s_add_i32 s24, s24, s25
	s_lshl_b32 s27, s26, 5
	s_add_u32 s30, s18, s27
	s_addc_u32 s31, s19, 0
	s_lshl_b32 s27, s26, 16
	s_add_u32 s28, s16, s27
	s_addc_u32 s29, s17, 0
	global_load_dword v52, v1, s[30:31]
	global_load_dword v53, v0, s[28:29]
	s_add_i32 s26, s15, s24
	s_add_i32 s24, s24, s25
	s_lshl_b32 s27, s26, 5
	s_add_u32 s30, s18, s27
	s_addc_u32 s31, s19, 0
	s_lshl_b32 s27, s26, 16
	s_add_u32 s28, s16, s27
	s_addc_u32 s29, s17, 0
	global_load_dword v54, v1, s[30:31]
	global_load_dword v55, v0, s[28:29]
	s_add_i32 s26, s15, s24
	s_add_i32 s24, s24, s25
	s_lshl_b32 s27, s26, 5
	s_add_u32 s30, s18, s27
	s_addc_u32 s31, s19, 0
	s_lshl_b32 s27, s26, 16
	s_add_u32 s28, s16, s27
	s_addc_u32 s29, s17, 0
	global_load_dword v56, v1, s[30:31]
	global_load_dword v57, v0, s[28:29]
	s_add_i32 s26, s15, s24
	s_add_i32 s24, s24, s25
	s_lshl_b32 s27, s26, 5
	s_add_u32 s30, s18, s27
	s_addc_u32 s31, s19, 0
	s_lshl_b32 s27, s26, 16
	s_add_u32 s28, s16, s27
	s_addc_u32 s29, s17, 0
	global_load_dword v58, v1, s[30:31]
	global_load_dword v59, v0, s[28:29]
	s_add_i32 s26, s15, s24
	s_add_i32 s24, s24, s25
	s_lshl_b32 s27, s26, 5
	s_add_u32 s30, s18, s27
	s_addc_u32 s31, s19, 0
	s_lshl_b32 s27, s26, 16
	s_add_u32 s28, s16, s27
	s_addc_u32 s29, s17, 0
	global_load_dword v62, v1, s[30:31]
	global_load_dword v63, v0, s[28:29]
	s_add_i32 s26, s15, s24
	s_add_i32 s24, s24, s25
	s_lshl_b32 s27, s26, 5
	s_add_u32 s30, s18, s27
	s_addc_u32 s31, s19, 0
	s_lshl_b32 s27, s26, 16
	s_add_u32 s28, s16, s27
	s_addc_u32 s29, s17, 0
	global_load_dword v68, v1, s[30:31]
	global_load_dword v69, v0, s[28:29]
	s_add_i32 s26, s15, s24
	s_add_i32 s24, s24, s25
	s_lshl_b32 s27, s26, 5
	s_add_u32 s30, s18, s27
	s_addc_u32 s31, s19, 0
	s_lshl_b32 s27, s26, 16
	s_add_u32 s28, s16, s27
	s_addc_u32 s29, s17, 0
	global_load_dword v70, v1, s[30:31]
	global_load_dword v71, v0, s[28:29]
	s_waitcnt vmcnt(50)
	s_add_i32 s26, s15, s24
	s_add_i32 s24, s24, s25
	s_lshl_b32 s27, s26, 5
	s_add_u32 s30, s18, s27
	s_addc_u32 s31, s19, 0
	s_lshl_b32 s27, s26, 16
	s_add_u32 s28, s16, s27
	s_addc_u32 s29, s17, 0
	global_load_dword v72, v1, s[30:31]
	global_load_dword v73, v0, s[28:29]
	s_add_i32 s26, s15, s24
	s_add_i32 s24, s24, s25
	s_lshl_b32 s27, s26, 5
	s_add_u32 s30, s18, s27
	s_addc_u32 s31, s19, 0
	s_lshl_b32 s27, s26, 16
	s_add_u32 s28, s16, s27
	s_addc_u32 s29, s17, 0
	global_load_dword v76, v1, s[30:31]
	global_load_dword v77, v0, s[28:29]
	s_add_i32 s26, s15, s24
	s_add_i32 s24, s24, s25
	s_lshl_b32 s27, s26, 5
	s_add_u32 s30, s18, s27
	s_addc_u32 s31, s19, 0
	s_lshl_b32 s27, s26, 16
	s_add_u32 s28, s16, s27
	s_addc_u32 s29, s17, 0
	global_load_dword v78, v1, s[30:31]
	global_load_dword v79, v0, s[28:29]
	s_add_i32 s26, s15, s20
	s_lshl_b32 s27, s26, 16
	s_add_u32 s28, s16, s27
	s_addc_u32 s29, s17, 0
	v_cvt_pk_bf16_f32 v60, v2, v3
	s_waitcnt vmcnt(63)
	v_lshlrev_b32_e32 v4, 16, v7
	v_and_b32_e32 v5, 0xffff0000, v7
	global_store_dword v0, v60, s[28:29]
	v_pk_fma_f32 v[2:3], v[2:3], v[6:7], v[4:5] op_sel_hi:[1,0,1]
	s_add_i32 s26, s15, s21
	s_lshl_b32 s27, s26, 16
	s_add_u32 s28, s16, s27
	s_addc_u32 s29, s17, 0
	v_cvt_pk_bf16_f32 v60, v2, v3
	s_waitcnt vmcnt(63)
	v_lshlrev_b32_e32 v4, 16, v9
	v_and_b32_e32 v5, 0xffff0000, v9
	global_store_dword v0, v60, s[28:29]
	v_pk_fma_f32 v[2:3], v[2:3], v[8:9], v[4:5] op_sel_hi:[1,0,1]
	s_add_i32 s26, s15, s5
	s_add_i32 s5, s5, s25
	s_lshl_b32 s27, s26, 16
	s_add_u32 s28, s16, s27
	s_addc_u32 s29, s17, 0
	v_cvt_pk_bf16_f32 v60, v2, v3
	s_waitcnt vmcnt(62)
	v_lshlrev_b32_e32 v4, 16, v11
	v_and_b32_e32 v5, 0xffff0000, v11
	global_store_dword v0, v60, s[28:29]
	v_pk_fma_f32 v[2:3], v[2:3], v[10:11], v[4:5] op_sel_hi:[1,0,1]
	s_add_i32 s26, s15, s5
	s_add_i32 s5, s5, s25
	s_lshl_b32 s27, s26, 16
	s_add_u32 s28, s16, s27
	s_addc_u32 s29, s17, 0
	v_cvt_pk_bf16_f32 v60, v2, v3
	s_waitcnt vmcnt(61)
	v_lshlrev_b32_e32 v4, 16, v13
	v_and_b32_e32 v5, 0xffff0000, v13
	global_store_dword v0, v60, s[28:29]
	v_pk_fma_f32 v[2:3], v[2:3], v[12:13], v[4:5] op_sel_hi:[1,0,1]
	s_add_i32 s26, s15, s5
	s_add_i32 s5, s5, s25
	s_lshl_b32 s27, s26, 16
	s_add_u32 s28, s16, s27
	s_addc_u32 s29, s17, 0
	v_cvt_pk_bf16_f32 v60, v2, v3
	s_waitcnt vmcnt(60)
	v_lshlrev_b32_e32 v4, 16, v15
	v_and_b32_e32 v5, 0xffff0000, v15
	global_store_dword v0, v60, s[28:29]
	v_pk_fma_f32 v[2:3], v[2:3], v[14:15], v[4:5] op_sel_hi:[1,0,1]
	s_add_i32 s26, s15, s5
	s_add_i32 s5, s5, s25
	s_lshl_b32 s27, s26, 16
	s_add_u32 s28, s16, s27
	s_addc_u32 s29, s17, 0
	v_cvt_pk_bf16_f32 v60, v2, v3
	s_waitcnt vmcnt(59)
	v_lshlrev_b32_e32 v4, 16, v17
	v_and_b32_e32 v5, 0xffff0000, v17
	global_store_dword v0, v60, s[28:29]
	v_pk_fma_f32 v[2:3], v[2:3], v[16:17], v[4:5] op_sel_hi:[1,0,1]
	s_add_i32 s26, s15, s5
	s_add_i32 s5, s5, s25
	s_lshl_b32 s27, s26, 16
	s_add_u32 s28, s16, s27
	s_addc_u32 s29, s17, 0
	v_cvt_pk_bf16_f32 v60, v2, v3
	s_waitcnt vmcnt(58)
	v_lshlrev_b32_e32 v4, 16, v19
	v_and_b32_e32 v5, 0xffff0000, v19
	global_store_dword v0, v60, s[28:29]
	v_pk_fma_f32 v[2:3], v[2:3], v[18:19], v[4:5] op_sel_hi:[1,0,1]
	s_add_i32 s26, s15, s5
	s_add_i32 s5, s5, s25
	s_lshl_b32 s27, s26, 16
	s_add_u32 s28, s16, s27
	s_addc_u32 s29, s17, 0
	v_cvt_pk_bf16_f32 v60, v2, v3
	s_waitcnt vmcnt(57)
	v_lshlrev_b32_e32 v4, 16, v21
	v_and_b32_e32 v5, 0xffff0000, v21
	global_store_dword v0, v60, s[28:29]
	v_pk_fma_f32 v[2:3], v[2:3], v[20:21], v[4:5] op_sel_hi:[1,0,1]
	s_add_i32 s26, s15, s5
	s_add_i32 s5, s5, s25
	s_lshl_b32 s27, s26, 16
	s_add_u32 s28, s16, s27
	s_addc_u32 s29, s17, 0
	v_cvt_pk_bf16_f32 v60, v2, v3
	s_waitcnt vmcnt(56)
	v_lshlrev_b32_e32 v4, 16, v23
	v_and_b32_e32 v5, 0xffff0000, v23
	global_store_dword v0, v60, s[28:29]
	v_pk_fma_f32 v[2:3], v[2:3], v[22:23], v[4:5] op_sel_hi:[1,0,1]
	s_add_i32 s26, s15, s5
	s_add_i32 s5, s5, s25
	s_lshl_b32 s27, s26, 16
	s_add_u32 s28, s16, s27
	s_addc_u32 s29, s17, 0
	v_cvt_pk_bf16_f32 v60, v2, v3
	s_waitcnt vmcnt(55)
	v_lshlrev_b32_e32 v4, 16, v25
	v_and_b32_e32 v5, 0xffff0000, v25
	global_store_dword v0, v60, s[28:29]
	v_pk_fma_f32 v[2:3], v[2:3], v[24:25], v[4:5] op_sel_hi:[1,0,1]
	s_add_i32 s26, s15, s5
	s_add_i32 s5, s5, s25
	s_lshl_b32 s27, s26, 16
	s_add_u32 s28, s16, s27
	s_addc_u32 s29, s17, 0
	v_cvt_pk_bf16_f32 v60, v2, v3
	s_waitcnt vmcnt(54)
	v_lshlrev_b32_e32 v4, 16, v27
	v_and_b32_e32 v5, 0xffff0000, v27
	global_store_dword v0, v60, s[28:29]
	v_pk_fma_f32 v[2:3], v[2:3], v[26:27], v[4:5] op_sel_hi:[1,0,1]
	s_add_i32 s26, s15, s5
	s_add_i32 s5, s5, s25
	s_lshl_b32 s27, s26, 16
	s_add_u32 s28, s16, s27
	s_addc_u32 s29, s17, 0
	v_cvt_pk_bf16_f32 v60, v2, v3
	s_waitcnt vmcnt(53)
	v_lshlrev_b32_e32 v4, 16, v29
	v_and_b32_e32 v5, 0xffff0000, v29
	global_store_dword v0, v60, s[28:29]
	v_pk_fma_f32 v[2:3], v[2:3], v[28:29], v[4:5] op_sel_hi:[1,0,1]
	s_add_i32 s26, s15, s5
	s_add_i32 s5, s5, s25
	s_lshl_b32 s27, s26, 16
	s_add_u32 s28, s16, s27
	s_addc_u32 s29, s17, 0
	v_cvt_pk_bf16_f32 v60, v2, v3
	s_waitcnt vmcnt(52)
	v_lshlrev_b32_e32 v4, 16, v31
	v_and_b32_e32 v5, 0xffff0000, v31
	global_store_dword v0, v60, s[28:29]
	v_pk_fma_f32 v[2:3], v[2:3], v[30:31], v[4:5] op_sel_hi:[1,0,1]
	s_add_i32 s26, s15, s5
	s_add_i32 s5, s5, s25
	s_lshl_b32 s27, s26, 16
	s_add_u32 s28, s16, s27
	s_addc_u32 s29, s17, 0
	v_cvt_pk_bf16_f32 v60, v2, v3
	s_waitcnt vmcnt(51)
	v_lshlrev_b32_e32 v4, 16, v33
	v_and_b32_e32 v5, 0xffff0000, v33
	global_store_dword v0, v60, s[28:29]
	v_pk_fma_f32 v[2:3], v[2:3], v[32:33], v[4:5] op_sel_hi:[1,0,1]
	s_add_i32 s26, s15, s5
	s_add_i32 s5, s5, s25
	s_lshl_b32 s27, s26, 16
	s_add_u32 s28, s16, s27
	s_addc_u32 s29, s17, 0
	v_cvt_pk_bf16_f32 v60, v2, v3
	s_waitcnt vmcnt(50)
	v_lshlrev_b32_e32 v4, 16, v35
	v_and_b32_e32 v5, 0xffff0000, v35
	global_store_dword v0, v60, s[28:29]
	v_pk_fma_f32 v[2:3], v[2:3], v[34:35], v[4:5] op_sel_hi:[1,0,1]
	s_add_i32 s26, s15, s5
	s_add_i32 s5, s5, s25
	s_lshl_b32 s27, s26, 16
	s_add_u32 s28, s16, s27
	s_addc_u32 s29, s17, 0
	v_cvt_pk_bf16_f32 v60, v2, v3
	s_waitcnt vmcnt(49)
	v_lshlrev_b32_e32 v4, 16, v37
	v_and_b32_e32 v5, 0xffff0000, v37
	global_store_dword v0, v60, s[28:29]
	v_pk_fma_f32 v[2:3], v[2:3], v[36:37], v[4:5] op_sel_hi:[1,0,1]
	s_add_i32 s26, s15, s5
	s_add_i32 s5, s5, s25
	s_lshl_b32 s27, s26, 16
	s_add_u32 s28, s16, s27
	s_addc_u32 s29, s17, 0
	v_cvt_pk_bf16_f32 v60, v2, v3
	s_waitcnt vmcnt(48)
	v_lshlrev_b32_e32 v4, 16, v39
	v_and_b32_e32 v5, 0xffff0000, v39
	global_store_dword v0, v60, s[28:29]
	v_pk_fma_f32 v[2:3], v[2:3], v[38:39], v[4:5] op_sel_hi:[1,0,1]
	s_add_i32 s26, s15, s5
	s_add_i32 s5, s5, s25
	s_lshl_b32 s27, s26, 16
	s_add_u32 s28, s16, s27
	s_addc_u32 s29, s17, 0
	v_cvt_pk_bf16_f32 v60, v2, v3
	s_waitcnt vmcnt(47)
	v_lshlrev_b32_e32 v4, 16, v41
	v_and_b32_e32 v5, 0xffff0000, v41
	global_store_dword v0, v60, s[28:29]
	v_pk_fma_f32 v[2:3], v[2:3], v[40:41], v[4:5] op_sel_hi:[1,0,1]
	s_add_i32 s26, s15, s5
	s_add_i32 s5, s5, s25
	s_lshl_b32 s27, s26, 16
	s_add_u32 s28, s16, s27
	s_addc_u32 s29, s17, 0
	v_cvt_pk_bf16_f32 v60, v2, v3
	s_waitcnt vmcnt(46)
	v_lshlrev_b32_e32 v4, 16, v43
	v_and_b32_e32 v5, 0xffff0000, v43
	global_store_dword v0, v60, s[28:29]
	v_pk_fma_f32 v[2:3], v[2:3], v[42:43], v[4:5] op_sel_hi:[1,0,1]
	s_add_i32 s26, s15, s5
	s_add_i32 s5, s5, s25
	s_lshl_b32 s27, s26, 16
	s_add_u32 s28, s16, s27
	s_addc_u32 s29, s17, 0
	v_cvt_pk_bf16_f32 v60, v2, v3
	s_waitcnt vmcnt(45)
	v_lshlrev_b32_e32 v4, 16, v45
	v_and_b32_e32 v5, 0xffff0000, v45
	global_store_dword v0, v60, s[28:29]
	v_pk_fma_f32 v[2:3], v[2:3], v[44:45], v[4:5] op_sel_hi:[1,0,1]
	s_add_i32 s26, s15, s5
	s_add_i32 s5, s5, s25
	s_lshl_b32 s27, s26, 16
	s_add_u32 s28, s16, s27
	s_addc_u32 s29, s17, 0
	v_cvt_pk_bf16_f32 v60, v2, v3
	s_waitcnt vmcnt(44)
	v_lshlrev_b32_e32 v4, 16, v47
	v_and_b32_e32 v5, 0xffff0000, v47
	global_store_dword v0, v60, s[28:29]
	v_pk_fma_f32 v[2:3], v[2:3], v[46:47], v[4:5] op_sel_hi:[1,0,1]
	s_add_i32 s26, s15, s5
	s_add_i32 s5, s5, s25
	s_lshl_b32 s27, s26, 16
	s_add_u32 s28, s16, s27
	s_addc_u32 s29, s17, 0
	v_cvt_pk_bf16_f32 v60, v2, v3
	s_waitcnt vmcnt(43)
	v_lshlrev_b32_e32 v4, 16, v49
	v_and_b32_e32 v5, 0xffff0000, v49
	global_store_dword v0, v60, s[28:29]
	v_pk_fma_f32 v[2:3], v[2:3], v[48:49], v[4:5] op_sel_hi:[1,0,1]
	s_add_i32 s26, s15, s5
	s_add_i32 s5, s5, s25
	s_lshl_b32 s27, s26, 16
	s_add_u32 s28, s16, s27
	s_addc_u32 s29, s17, 0
	v_cvt_pk_bf16_f32 v60, v2, v3
	s_waitcnt vmcnt(42)
	v_lshlrev_b32_e32 v4, 16, v51
	v_and_b32_e32 v5, 0xffff0000, v51
	global_store_dword v0, v60, s[28:29]
	v_pk_fma_f32 v[2:3], v[2:3], v[50:51], v[4:5] op_sel_hi:[1,0,1]
	s_add_i32 s26, s15, s5
	s_add_i32 s5, s5, s25
	s_lshl_b32 s27, s26, 16
	s_add_u32 s28, s16, s27
	s_addc_u32 s29, s17, 0
	v_cvt_pk_bf16_f32 v60, v2, v3
	s_waitcnt vmcnt(41)
	v_lshlrev_b32_e32 v4, 16, v53
	v_and_b32_e32 v5, 0xffff0000, v53
	global_store_dword v0, v60, s[28:29]
	v_pk_fma_f32 v[2:3], v[2:3], v[52:53], v[4:5] op_sel_hi:[1,0,1]
	s_add_i32 s26, s15, s5
	s_add_i32 s5, s5, s25
	s_lshl_b32 s27, s26, 16
	s_add_u32 s28, s16, s27
	s_addc_u32 s29, s17, 0
	v_cvt_pk_bf16_f32 v60, v2, v3
	s_waitcnt vmcnt(40)
	v_lshlrev_b32_e32 v4, 16, v55
	v_and_b32_e32 v5, 0xffff0000, v55
	global_store_dword v0, v60, s[28:29]
	v_pk_fma_f32 v[2:3], v[2:3], v[54:55], v[4:5] op_sel_hi:[1,0,1]
	s_add_i32 s26, s15, s5
	s_add_i32 s5, s5, s25
	s_lshl_b32 s27, s26, 16
	s_add_u32 s28, s16, s27
	s_addc_u32 s29, s17, 0
	v_cvt_pk_bf16_f32 v60, v2, v3
	s_waitcnt vmcnt(39)
	v_lshlrev_b32_e32 v4, 16, v57
	v_and_b32_e32 v5, 0xffff0000, v57
	global_store_dword v0, v60, s[28:29]
	v_pk_fma_f32 v[2:3], v[2:3], v[56:57], v[4:5] op_sel_hi:[1,0,1]
	s_add_i32 s26, s15, s5
	s_add_i32 s5, s5, s25
	s_lshl_b32 s27, s26, 16
	s_add_u32 s28, s16, s27
	s_addc_u32 s29, s17, 0
	v_cvt_pk_bf16_f32 v60, v2, v3
	s_waitcnt vmcnt(38)
	v_lshlrev_b32_e32 v4, 16, v59
	v_and_b32_e32 v5, 0xffff0000, v59
	global_store_dword v0, v60, s[28:29]
	v_pk_fma_f32 v[2:3], v[2:3], v[58:59], v[4:5] op_sel_hi:[1,0,1]
	s_add_i32 s26, s15, s5
	s_add_i32 s5, s5, s25
	s_lshl_b32 s27, s26, 16
	s_add_u32 s28, s16, s27
	s_addc_u32 s29, s17, 0
	v_cvt_pk_bf16_f32 v60, v2, v3
	s_waitcnt vmcnt(37)
	v_lshlrev_b32_e32 v4, 16, v63
	v_and_b32_e32 v5, 0xffff0000, v63
	global_store_dword v0, v60, s[28:29]
	v_pk_fma_f32 v[2:3], v[2:3], v[62:63], v[4:5] op_sel_hi:[1,0,1]
	s_add_i32 s26, s15, s5
	s_add_i32 s5, s5, s25
	s_lshl_b32 s27, s26, 16
	s_add_u32 s28, s16, s27
	s_addc_u32 s29, s17, 0
	v_cvt_pk_bf16_f32 v60, v2, v3
	s_waitcnt vmcnt(36)
	v_lshlrev_b32_e32 v4, 16, v69
	v_and_b32_e32 v5, 0xffff0000, v69
	global_store_dword v0, v60, s[28:29]
	v_pk_fma_f32 v[2:3], v[2:3], v[68:69], v[4:5] op_sel_hi:[1,0,1]
	s_add_i32 s26, s15, s5
	s_add_i32 s5, s5, s25
	s_lshl_b32 s27, s26, 16
	s_add_u32 s28, s16, s27
	s_addc_u32 s29, s17, 0
	v_cvt_pk_bf16_f32 v60, v2, v3
	s_waitcnt vmcnt(35)
	v_lshlrev_b32_e32 v4, 16, v71
	v_and_b32_e32 v5, 0xffff0000, v71
	global_store_dword v0, v60, s[28:29]
	v_pk_fma_f32 v[2:3], v[2:3], v[70:71], v[4:5] op_sel_hi:[1,0,1]
	s_add_i32 s26, s15, s5
	s_add_i32 s5, s5, s25
	s_lshl_b32 s27, s26, 16
	s_add_u32 s28, s16, s27
	s_addc_u32 s29, s17, 0
	v_cvt_pk_bf16_f32 v60, v2, v3
	s_waitcnt vmcnt(34)
	v_lshlrev_b32_e32 v4, 16, v73
	v_and_b32_e32 v5, 0xffff0000, v73
	global_store_dword v0, v60, s[28:29]
	v_pk_fma_f32 v[2:3], v[2:3], v[72:73], v[4:5] op_sel_hi:[1,0,1]
	s_add_i32 s26, s15, s5
	s_add_i32 s5, s5, s25
	s_lshl_b32 s27, s26, 16
	s_add_u32 s28, s16, s27
	s_addc_u32 s29, s17, 0
	v_cvt_pk_bf16_f32 v60, v2, v3
	s_waitcnt vmcnt(33)
	v_lshlrev_b32_e32 v4, 16, v77
	v_and_b32_e32 v5, 0xffff0000, v77
	global_store_dword v0, v60, s[28:29]
	v_pk_fma_f32 v[2:3], v[2:3], v[76:77], v[4:5] op_sel_hi:[1,0,1]
	s_add_i32 s26, s15, s5
	s_add_i32 s5, s5, s25
	s_lshl_b32 s27, s26, 16
	s_add_u32 s28, s16, s27
	s_addc_u32 s29, s17, 0
	v_cvt_pk_bf16_f32 v60, v2, v3
	s_waitcnt vmcnt(32)
	v_lshlrev_b32_e32 v4, 16, v79
	v_and_b32_e32 v5, 0xffff0000, v79
	global_store_dword v0, v60, s[28:29]
	v_pk_fma_f32 v[2:3], v[2:3], v[78:79], v[4:5] op_sel_hi:[1,0,1]
	s_add_i32 s26, s15, s5
	s_add_i32 s5, s5, s25
	s_lshl_b32 s27, s26, 16
	s_add_u32 s28, s16, s27
	s_addc_u32 s29, s17, 0
	v_cvt_pk_bf16_f32 v60, v2, v3
	global_store_dword v0, v60, s[28:29]
	s_add_i32 s9, s9, s33
	s_add_i32 s7, s7, s8
	s_cmpk_lt_i32 s9, 0x200
	s_waitcnt vmcnt(0)
	s_cbranch_scc1 .LBB0_673

.LBB0_2137:
	s_and_b32 s4, s9, 0x700
	v_and_b32_e32 v0, 0xff, v164
	v_or_b32_e32 v0, s4, v0
	v_lshlrev_b32_e32 v0, 2, v0
	s_bfe_u32 s12, s11, 0x30003
	s_bfe_u32 s13, s11, 0x20006
	s_lshr_b32 s14, s11, 8
	s_lshl_b32 s15, s14, 2
	s_or_b32 s15, s15, s13
	s_mul_i32 s15, s15, 34
	s_lshl_b32 s4, s12, 13
	s_add_u32 s16, s0, s4
	s_addc_u32 s17, s1, 0
	s_lshl_b32 s4, s12, 2
	s_add_u32 s18, s2, s4
	s_addc_u32 s19, s8, 0
	s_cmp_eq_u32 s14, 0
	s_cselect_b32 s20, 0, 1
	s_cselect_b32 s21, 1, 0
	s_cselect_b32 s24, 2, 33
	s_cselect_b32 s25, 1, -1
	s_mov_b32 s5, s24
	v_mov_b32_e32 v2, 0
	v_mov_b32_e32 v3, 0
	s_waitcnt vmcnt(0)
	s_add_i32 s26, s15, s20
	s_lshl_b32 s27, s26, 5
	s_add_u32 s30, s18, s27
	s_addc_u32 s31, s19, 0
	s_lshl_b32 s27, s26, 16
	s_add_u32 s28, s16, s27
	s_addc_u32 s29, s17, 0
	global_load_dword v6, v1, s[30:31]
	global_load_dword v7, v0, s[28:29]
	s_add_i32 s26, s15, s21
	s_lshl_b32 s27, s26, 5
	s_add_u32 s30, s18, s27
	s_addc_u32 s31, s19, 0
	s_lshl_b32 s27, s26, 16
	s_add_u32 s28, s16, s27
	s_addc_u32 s29, s17, 0
	global_load_dword v8, v1, s[30:31]
	global_load_dword v9, v0, s[28:29]
	s_add_i32 s26, s15, s24
	s_add_i32 s24, s24, s25
	s_lshl_b32 s27, s26, 5
	s_add_u32 s30, s18, s27
	s_addc_u32 s31, s19, 0
	s_lshl_b32 s27, s26, 16
	s_add_u32 s28, s16, s27
	s_addc_u32 s29, s17, 0
	global_load_dword v10, v1, s[30:31]
	global_load_dword v11, v0, s[28:29]
	s_add_i32 s26, s15, s24
	s_add_i32 s24, s24, s25
	s_lshl_b32 s27, s26, 5
	s_add_u32 s30, s18, s27
	s_addc_u32 s31, s19, 0
	s_lshl_b32 s27, s26, 16
	s_add_u32 s28, s16, s27
	s_addc_u32 s29, s17, 0
	global_load_dword v12, v1, s[30:31]
	global_load_dword v13, v0, s[28:29]
	s_add_i32 s26, s15, s24
	s_add_i32 s24, s24, s25
	s_lshl_b32 s27, s26, 5
	s_add_u32 s30, s18, s27
	s_addc_u32 s31, s19, 0
	s_lshl_b32 s27, s26, 16
	s_add_u32 s28, s16, s27
	s_addc_u32 s29, s17, 0
	global_load_dword v14, v1, s[30:31]
	global_load_dword v15, v0, s[28:29]
	s_add_i32 s26, s15, s24
	s_add_i32 s24, s24, s25
	s_lshl_b32 s27, s26, 5
	s_add_u32 s30, s18, s27
	s_addc_u32 s31, s19, 0
	s_lshl_b32 s27, s26, 16
	s_add_u32 s28, s16, s27
	s_addc_u32 s29, s17, 0
	global_load_dword v16, v1, s[30:31]
	global_load_dword v17, v0, s[28:29]
	s_add_i32 s26, s15, s24
	s_add_i32 s24, s24, s25
	s_lshl_b32 s27, s26, 5
	s_add_u32 s30, s18, s27
	s_addc_u32 s31, s19, 0
	s_lshl_b32 s27, s26, 16
	s_add_u32 s28, s16, s27
	s_addc_u32 s29, s17, 0
	global_load_dword v18, v1, s[30:31]
	global_load_dword v19, v0, s[28:29]
	s_add_i32 s26, s15, s24
	s_add_i32 s24, s24, s25
	s_lshl_b32 s27, s26, 5
	s_add_u32 s30, s18, s27
	s_addc_u32 s31, s19, 0
	s_lshl_b32 s27, s26, 16
	s_add_u32 s28, s16, s27
	s_addc_u32 s29, s17, 0
	global_load_dword v20, v1, s[30:31]
	global_load_dword v21, v0, s[28:29]
	s_add_i32 s26, s15, s24
	s_add_i32 s24, s24, s25
	s_lshl_b32 s27, s26, 5
	s_add_u32 s30, s18, s27
	s_addc_u32 s31, s19, 0
	s_lshl_b32 s27, s26, 16
	s_add_u32 s28, s16, s27
	s_addc_u32 s29, s17, 0
	global_load_dword v22, v1, s[30:31]
	global_load_dword v23, v0, s[28:29]
	s_add_i32 s26, s15, s24
	s_add_i32 s24, s24, s25
	s_lshl_b32 s27, s26, 5
	s_add_u32 s30, s18, s27
	s_addc_u32 s31, s19, 0
	s_lshl_b32 s27, s26, 16
	s_add_u32 s28, s16, s27
	s_addc_u32 s29, s17, 0
	global_load_dword v24, v1, s[30:31]
	global_load_dword v25, v0, s[28:29]
	s_add_i32 s26, s15, s24
	s_add_i32 s24, s24, s25
	s_lshl_b32 s27, s26, 5
	s_add_u32 s30, s18, s27
	s_addc_u32 s31, s19, 0
	s_lshl_b32 s27, s26, 16
	s_add_u32 s28, s16, s27
	s_addc_u32 s29, s17, 0
	global_load_dword v26, v1, s[30:31]
	global_load_dword v27, v0, s[28:29]
	s_add_i32 s26, s15, s24
	s_add_i32 s24, s24, s25
	s_lshl_b32 s27, s26, 5
	s_add_u32 s30, s18, s27
	s_addc_u32 s31, s19, 0
	s_lshl_b32 s27, s26, 16
	s_add_u32 s28, s16, s27
	s_addc_u32 s29, s17, 0
	global_load_dword v28, v1, s[30:31]
	global_load_dword v29, v0, s[28:29]
	s_add_i32 s26, s15, s24
	s_add_i32 s24, s24, s25
	s_lshl_b32 s27, s26, 5
	s_add_u32 s30, s18, s27
	s_addc_u32 s31, s19, 0
	s_lshl_b32 s27, s26, 16
	s_add_u32 s28, s16, s27
	s_addc_u32 s29, s17, 0
	global_load_dword v30, v1, s[30:31]
	global_load_dword v31, v0, s[28:29]
	s_add_i32 s26, s15, s24
	s_add_i32 s24, s24, s25
	s_lshl_b32 s27, s26, 5
	s_add_u32 s30, s18, s27
	s_addc_u32 s31, s19, 0
	s_lshl_b32 s27, s26, 16
	s_add_u32 s28, s16, s27
	s_addc_u32 s29, s17, 0
	global_load_dword v32, v1, s[30:31]
	global_load_dword v33, v0, s[28:29]
	s_add_i32 s26, s15, s24
	s_add_i32 s24, s24, s25
	s_lshl_b32 s27, s26, 5
	s_add_u32 s30, s18, s27
	s_addc_u32 s31, s19, 0
	s_lshl_b32 s27, s26, 16
	s_add_u32 s28, s16, s27
	s_addc_u32 s29, s17, 0
	global_load_dword v34, v1, s[30:31]
	global_load_dword v35, v0, s[28:29]
	s_add_i32 s26, s15, s24
	s_add_i32 s24, s24, s25
	s_lshl_b32 s27, s26, 5
	s_add_u32 s30, s18, s27
	s_addc_u32 s31, s19, 0
	s_lshl_b32 s27, s26, 16
	s_add_u32 s28, s16, s27
	s_addc_u32 s29, s17, 0
	global_load_dword v36, v1, s[30:31]
	global_load_dword v37, v0, s[28:29]
	s_add_i32 s26, s15, s24
	s_add_i32 s24, s24, s25
	s_lshl_b32 s27, s26, 5
	s_add_u32 s30, s18, s27
	s_addc_u32 s31, s19, 0
	s_lshl_b32 s27, s26, 16
	s_add_u32 s28, s16, s27
	s_addc_u32 s29, s17, 0
	global_load_dword v38, v1, s[30:31]
	global_load_dword v39, v0, s[28:29]
	s_add_i32 s26, s15, s24
	s_add_i32 s24, s24, s25
	s_lshl_b32 s27, s26, 5
	s_add_u32 s30, s18, s27
	s_addc_u32 s31, s19, 0
	s_lshl_b32 s27, s26, 16
	s_add_u32 s28, s16, s27
	s_addc_u32 s29, s17, 0
	global_load_dword v40, v1, s[30:31]
	global_load_dword v41, v0, s[28:29]
	s_add_i32 s26, s15, s24
	s_add_i32 s24, s24, s25
	s_lshl_b32 s27, s26, 5
	s_add_u32 s30, s18, s27
	s_addc_u32 s31, s19, 0
	s_lshl_b32 s27, s26, 16
	s_add_u32 s28, s16, s27
	s_addc_u32 s29, s17, 0
	global_load_dword v42, v1, s[30:31]
	global_load_dword v43, v0, s[28:29]
	s_add_i32 s26, s15, s24
	s_add_i32 s24, s24, s25
	s_lshl_b32 s27, s26, 5
	s_add_u32 s30, s18, s27
	s_addc_u32 s31, s19, 0
	s_lshl_b32 s27, s26, 16
	s_add_u32 s28, s16, s27
	s_addc_u32 s29, s17, 0
	global_load_dword v44, v1, s[30:31]
	global_load_dword v45, v0, s[28:29]
	s_add_i32 s26, s15, s24
	s_add_i32 s24, s24, s25
	s_lshl_b32 s27, s26, 5
	s_add_u32 s30, s18, s27
	s_addc_u32 s31, s19, 0
	s_lshl_b32 s27, s26, 16
	s_add_u32 s28, s16, s27
	s_addc_u32 s29, s17, 0
	global_load_dword v46, v1, s[30:31]
	global_load_dword v47, v0, s[28:29]
	s_add_i32 s26, s15, s24
	s_add_i32 s24, s24, s25
	s_lshl_b32 s27, s26, 5
	s_add_u32 s30, s18, s27
	s_addc_u32 s31, s19, 0
	s_lshl_b32 s27, s26, 16
	s_add_u32 s28, s16, s27
	s_addc_u32 s29, s17, 0
	global_load_dword v48, v1, s[30:31]
	global_load_dword v49, v0, s[28:29]
	s_add_i32 s26, s15, s24
	s_add_i32 s24, s24, s25
	s_lshl_b32 s27, s26, 5
	s_add_u32 s30, s18, s27
	s_addc_u32 s31, s19, 0
	s_lshl_b32 s27, s26, 16
	s_add_u32 s28, s16, s27
	s_addc_u32 s29, s17, 0
	global_load_dword v50, v1, s[30:31]
	global_load_dword v51, v0, s[28:29]
	s_add_i32 s26, s15, s24
	s_add_i32 s24, s24, s25
	s_lshl_b32 s27, s26, 5
	s_add_u32 s30, s18, s27
	s_addc_u32 s31, s19, 0
	s_lshl_b32 s27, s26, 16
	s_add_u32 s28, s16, s27
	s_addc_u32 s29, s17, 0
	global_load_dword v52, v1, s[30:31]
	global_load_dword v53, v0, s[28:29]
	s_add_i32 s26, s15, s24
	s_add_i32 s24, s24, s25
	s_lshl_b32 s27, s26, 5
	s_add_u32 s30, s18, s27
	s_addc_u32 s31, s19, 0
	s_lshl_b32 s27, s26, 16
	s_add_u32 s28, s16, s27
	s_addc_u32 s29, s17, 0
	global_load_dword v54, v1, s[30:31]
	global_load_dword v55, v0, s[28:29]
	s_add_i32 s26, s15, s24
	s_add_i32 s24, s24, s25
	s_lshl_b32 s27, s26, 5
	s_add_u32 s30, s18, s27
	s_addc_u32 s31, s19, 0
	s_lshl_b32 s27, s26, 16
	s_add_u32 s28, s16, s27
	s_addc_u32 s29, s17, 0
	global_load_dword v56, v1, s[30:31]
	global_load_dword v57, v0, s[28:29]
	s_add_i32 s26, s15, s24
	s_add_i32 s24, s24, s25
	s_lshl_b32 s27, s26, 5
	s_add_u32 s30, s18, s27
	s_addc_u32 s31, s19, 0
	s_lshl_b32 s27, s26, 16
	s_add_u32 s28, s16, s27
	s_addc_u32 s29, s17, 0
	global_load_dword v58, v1, s[30:31]
	global_load_dword v59, v0, s[28:29]
	s_add_i32 s26, s15, s24
	s_add_i32 s24, s24, s25
	s_lshl_b32 s27, s26, 5
	s_add_u32 s30, s18, s27
	s_addc_u32 s31, s19, 0
	s_lshl_b32 s27, s26, 16
	s_add_u32 s28, s16, s27
	s_addc_u32 s29, s17, 0
	global_load_dword v62, v1, s[30:31]
	global_load_dword v63, v0, s[28:29]
	s_add_i32 s26, s15, s24
	s_add_i32 s24, s24, s25
	s_lshl_b32 s27, s26, 5
	s_add_u32 s30, s18, s27
	s_addc_u32 s31, s19, 0
	s_lshl_b32 s27, s26, 16
	s_add_u32 s28, s16, s27
	s_addc_u32 s29, s17, 0
	global_load_dword v68, v1, s[30:31]
	global_load_dword v69, v0, s[28:29]
	s_add_i32 s26, s15, s24
	s_add_i32 s24, s24, s25
	s_lshl_b32 s27, s26, 5
	s_add_u32 s30, s18, s27
	s_addc_u32 s31, s19, 0
	s_lshl_b32 s27, s26, 16
	s_add_u32 s28, s16, s27
	s_addc_u32 s29, s17, 0
	global_load_dword v70, v1, s[30:31]
	global_load_dword v71, v0, s[28:29]
	s_waitcnt vmcnt(50)
	s_add_i32 s26, s15, s24
	s_add_i32 s24, s24, s25
	s_lshl_b32 s27, s26, 5
	s_add_u32 s30, s18, s27
	s_addc_u32 s31, s19, 0
	s_lshl_b32 s27, s26, 16
	s_add_u32 s28, s16, s27
	s_addc_u32 s29, s17, 0
	global_load_dword v72, v1, s[30:31]
	global_load_dword v73, v0, s[28:29]
	s_add_i32 s26, s15, s24
	s_add_i32 s24, s24, s25
	s_lshl_b32 s27, s26, 5
	s_add_u32 s30, s18, s27
	s_addc_u32 s31, s19, 0
	s_lshl_b32 s27, s26, 16
	s_add_u32 s28, s16, s27
	s_addc_u32 s29, s17, 0
	global_load_dword v76, v1, s[30:31]
	global_load_dword v77, v0, s[28:29]
	s_add_i32 s26, s15, s24
	s_add_i32 s24, s24, s25
	s_lshl_b32 s27, s26, 5
	s_add_u32 s30, s18, s27
	s_addc_u32 s31, s19, 0
	s_lshl_b32 s27, s26, 16
	s_add_u32 s28, s16, s27
	s_addc_u32 s29, s17, 0
	global_load_dword v78, v1, s[30:31]
	global_load_dword v79, v0, s[28:29]
	s_add_i32 s26, s15, s20
	s_lshl_b32 s27, s26, 16
	s_add_u32 s28, s16, s27
	s_addc_u32 s29, s17, 0
	v_cvt_pk_bf16_f32 v60, v2, v3
	s_waitcnt vmcnt(63)
	v_lshlrev_b32_e32 v4, 16, v7
	v_and_b32_e32 v5, 0xffff0000, v7
	global_store_dword v0, v60, s[28:29]
	v_pk_fma_f32 v[2:3], v[2:3], v[6:7], v[4:5] op_sel_hi:[1,0,1]
	s_add_i32 s26, s15, s21
	s_lshl_b32 s27, s26, 16
	s_add_u32 s28, s16, s27
	s_addc_u32 s29, s17, 0
	v_cvt_pk_bf16_f32 v60, v2, v3
	s_waitcnt vmcnt(63)
	v_lshlrev_b32_e32 v4, 16, v9
	v_and_b32_e32 v5, 0xffff0000, v9
	global_store_dword v0, v60, s[28:29]
	v_pk_fma_f32 v[2:3], v[2:3], v[8:9], v[4:5] op_sel_hi:[1,0,1]
	s_add_i32 s26, s15, s5
	s_add_i32 s5, s5, s25
	s_lshl_b32 s27, s26, 16
	s_add_u32 s28, s16, s27
	s_addc_u32 s29, s17, 0
	v_cvt_pk_bf16_f32 v60, v2, v3
	s_waitcnt vmcnt(62)
	v_lshlrev_b32_e32 v4, 16, v11
	v_and_b32_e32 v5, 0xffff0000, v11
	global_store_dword v0, v60, s[28:29]
	v_pk_fma_f32 v[2:3], v[2:3], v[10:11], v[4:5] op_sel_hi:[1,0,1]
	s_add_i32 s26, s15, s5
	s_add_i32 s5, s5, s25
	s_lshl_b32 s27, s26, 16
	s_add_u32 s28, s16, s27
	s_addc_u32 s29, s17, 0
	v_cvt_pk_bf16_f32 v60, v2, v3
	s_waitcnt vmcnt(61)
	v_lshlrev_b32_e32 v4, 16, v13
	v_and_b32_e32 v5, 0xffff0000, v13
	global_store_dword v0, v60, s[28:29]
	v_pk_fma_f32 v[2:3], v[2:3], v[12:13], v[4:5] op_sel_hi:[1,0,1]
	s_add_i32 s26, s15, s5
	s_add_i32 s5, s5, s25
	s_lshl_b32 s27, s26, 16
	s_add_u32 s28, s16, s27
	s_addc_u32 s29, s17, 0
	v_cvt_pk_bf16_f32 v60, v2, v3
	s_waitcnt vmcnt(60)
	v_lshlrev_b32_e32 v4, 16, v15
	v_and_b32_e32 v5, 0xffff0000, v15
	global_store_dword v0, v60, s[28:29]
	v_pk_fma_f32 v[2:3], v[2:3], v[14:15], v[4:5] op_sel_hi:[1,0,1]
	s_add_i32 s26, s15, s5
	s_add_i32 s5, s5, s25
	s_lshl_b32 s27, s26, 16
	s_add_u32 s28, s16, s27
	s_addc_u32 s29, s17, 0
	v_cvt_pk_bf16_f32 v60, v2, v3
	s_waitcnt vmcnt(59)
	v_lshlrev_b32_e32 v4, 16, v17
	v_and_b32_e32 v5, 0xffff0000, v17
	global_store_dword v0, v60, s[28:29]
	v_pk_fma_f32 v[2:3], v[2:3], v[16:17], v[4:5] op_sel_hi:[1,0,1]
	s_add_i32 s26, s15, s5
	s_add_i32 s5, s5, s25
	s_lshl_b32 s27, s26, 16
	s_add_u32 s28, s16, s27
	s_addc_u32 s29, s17, 0
	v_cvt_pk_bf16_f32 v60, v2, v3
	s_waitcnt vmcnt(58)
	v_lshlrev_b32_e32 v4, 16, v19
	v_and_b32_e32 v5, 0xffff0000, v19
	global_store_dword v0, v60, s[28:29]
	v_pk_fma_f32 v[2:3], v[2:3], v[18:19], v[4:5] op_sel_hi:[1,0,1]
	s_add_i32 s26, s15, s5
	s_add_i32 s5, s5, s25
	s_lshl_b32 s27, s26, 16
	s_add_u32 s28, s16, s27
	s_addc_u32 s29, s17, 0
	v_cvt_pk_bf16_f32 v60, v2, v3
	s_waitcnt vmcnt(57)
	v_lshlrev_b32_e32 v4, 16, v21
	v_and_b32_e32 v5, 0xffff0000, v21
	global_store_dword v0, v60, s[28:29]
	v_pk_fma_f32 v[2:3], v[2:3], v[20:21], v[4:5] op_sel_hi:[1,0,1]
	s_add_i32 s26, s15, s5
	s_add_i32 s5, s5, s25
	s_lshl_b32 s27, s26, 16
	s_add_u32 s28, s16, s27
	s_addc_u32 s29, s17, 0
	v_cvt_pk_bf16_f32 v60, v2, v3
	s_waitcnt vmcnt(56)
	v_lshlrev_b32_e32 v4, 16, v23
	v_and_b32_e32 v5, 0xffff0000, v23
	global_store_dword v0, v60, s[28:29]
	v_pk_fma_f32 v[2:3], v[2:3], v[22:23], v[4:5] op_sel_hi:[1,0,1]
	s_add_i32 s26, s15, s5
	s_add_i32 s5, s5, s25
	s_lshl_b32 s27, s26, 16
	s_add_u32 s28, s16, s27
	s_addc_u32 s29, s17, 0
	v_cvt_pk_bf16_f32 v60, v2, v3
	s_waitcnt vmcnt(55)
	v_lshlrev_b32_e32 v4, 16, v25
	v_and_b32_e32 v5, 0xffff0000, v25
	global_store_dword v0, v60, s[28:29]
	v_pk_fma_f32 v[2:3], v[2:3], v[24:25], v[4:5] op_sel_hi:[1,0,1]
	s_add_i32 s26, s15, s5
	s_add_i32 s5, s5, s25
	s_lshl_b32 s27, s26, 16
	s_add_u32 s28, s16, s27
	s_addc_u32 s29, s17, 0
	v_cvt_pk_bf16_f32 v60, v2, v3
	s_waitcnt vmcnt(54)
	v_lshlrev_b32_e32 v4, 16, v27
	v_and_b32_e32 v5, 0xffff0000, v27
	global_store_dword v0, v60, s[28:29]
	v_pk_fma_f32 v[2:3], v[2:3], v[26:27], v[4:5] op_sel_hi:[1,0,1]
	s_add_i32 s26, s15, s5
	s_add_i32 s5, s5, s25
	s_lshl_b32 s27, s26, 16
	s_add_u32 s28, s16, s27
	s_addc_u32 s29, s17, 0
	v_cvt_pk_bf16_f32 v60, v2, v3
	s_waitcnt vmcnt(53)
	v_lshlrev_b32_e32 v4, 16, v29
	v_and_b32_e32 v5, 0xffff0000, v29
	global_store_dword v0, v60, s[28:29]
	v_pk_fma_f32 v[2:3], v[2:3], v[28:29], v[4:5] op_sel_hi:[1,0,1]
	s_add_i32 s26, s15, s5
	s_add_i32 s5, s5, s25
	s_lshl_b32 s27, s26, 16
	s_add_u32 s28, s16, s27
	s_addc_u32 s29, s17, 0
	v_cvt_pk_bf16_f32 v60, v2, v3
	s_waitcnt vmcnt(52)
	v_lshlrev_b32_e32 v4, 16, v31
	v_and_b32_e32 v5, 0xffff0000, v31
	global_store_dword v0, v60, s[28:29]
	v_pk_fma_f32 v[2:3], v[2:3], v[30:31], v[4:5] op_sel_hi:[1,0,1]
	s_add_i32 s26, s15, s5
	s_add_i32 s5, s5, s25
	s_lshl_b32 s27, s26, 16
	s_add_u32 s28, s16, s27
	s_addc_u32 s29, s17, 0
	v_cvt_pk_bf16_f32 v60, v2, v3
	s_waitcnt vmcnt(51)
	v_lshlrev_b32_e32 v4, 16, v33
	v_and_b32_e32 v5, 0xffff0000, v33
	global_store_dword v0, v60, s[28:29]
	v_pk_fma_f32 v[2:3], v[2:3], v[32:33], v[4:5] op_sel_hi:[1,0,1]
	s_add_i32 s26, s15, s5
	s_add_i32 s5, s5, s25
	s_lshl_b32 s27, s26, 16
	s_add_u32 s28, s16, s27
	s_addc_u32 s29, s17, 0
	v_cvt_pk_bf16_f32 v60, v2, v3
	s_waitcnt vmcnt(50)
	v_lshlrev_b32_e32 v4, 16, v35
	v_and_b32_e32 v5, 0xffff0000, v35
	global_store_dword v0, v60, s[28:29]
	v_pk_fma_f32 v[2:3], v[2:3], v[34:35], v[4:5] op_sel_hi:[1,0,1]
	s_add_i32 s26, s15, s5
	s_add_i32 s5, s5, s25
	s_lshl_b32 s27, s26, 16
	s_add_u32 s28, s16, s27
	s_addc_u32 s29, s17, 0
	v_cvt_pk_bf16_f32 v60, v2, v3
	s_waitcnt vmcnt(49)
	v_lshlrev_b32_e32 v4, 16, v37
	v_and_b32_e32 v5, 0xffff0000, v37
	global_store_dword v0, v60, s[28:29]
	v_pk_fma_f32 v[2:3], v[2:3], v[36:37], v[4:5] op_sel_hi:[1,0,1]
	s_add_i32 s26, s15, s5
	s_add_i32 s5, s5, s25
	s_lshl_b32 s27, s26, 16
	s_add_u32 s28, s16, s27
	s_addc_u32 s29, s17, 0
	v_cvt_pk_bf16_f32 v60, v2, v3
	s_waitcnt vmcnt(48)
	v_lshlrev_b32_e32 v4, 16, v39
	v_and_b32_e32 v5, 0xffff0000, v39
	global_store_dword v0, v60, s[28:29]
	v_pk_fma_f32 v[2:3], v[2:3], v[38:39], v[4:5] op_sel_hi:[1,0,1]
	s_add_i32 s26, s15, s5
	s_add_i32 s5, s5, s25
	s_lshl_b32 s27, s26, 16
	s_add_u32 s28, s16, s27
	s_addc_u32 s29, s17, 0
	v_cvt_pk_bf16_f32 v60, v2, v3
	s_waitcnt vmcnt(47)
	v_lshlrev_b32_e32 v4, 16, v41
	v_and_b32_e32 v5, 0xffff0000, v41
	global_store_dword v0, v60, s[28:29]
	v_pk_fma_f32 v[2:3], v[2:3], v[40:41], v[4:5] op_sel_hi:[1,0,1]
	s_add_i32 s26, s15, s5
	s_add_i32 s5, s5, s25
	s_lshl_b32 s27, s26, 16
	s_add_u32 s28, s16, s27
	s_addc_u32 s29, s17, 0
	v_cvt_pk_bf16_f32 v60, v2, v3
	s_waitcnt vmcnt(46)
	v_lshlrev_b32_e32 v4, 16, v43
	v_and_b32_e32 v5, 0xffff0000, v43
	global_store_dword v0, v60, s[28:29]
	v_pk_fma_f32 v[2:3], v[2:3], v[42:43], v[4:5] op_sel_hi:[1,0,1]
	s_add_i32 s26, s15, s5
	s_add_i32 s5, s5, s25
	s_lshl_b32 s27, s26, 16
	s_add_u32 s28, s16, s27
	s_addc_u32 s29, s17, 0
	v_cvt_pk_bf16_f32 v60, v2, v3
	s_waitcnt vmcnt(45)
	v_lshlrev_b32_e32 v4, 16, v45
	v_and_b32_e32 v5, 0xffff0000, v45
	global_store_dword v0, v60, s[28:29]
	v_pk_fma_f32 v[2:3], v[2:3], v[44:45], v[4:5] op_sel_hi:[1,0,1]
	s_add_i32 s26, s15, s5
	s_add_i32 s5, s5, s25
	s_lshl_b32 s27, s26, 16
	s_add_u32 s28, s16, s27
	s_addc_u32 s29, s17, 0
	v_cvt_pk_bf16_f32 v60, v2, v3
	s_waitcnt vmcnt(44)
	v_lshlrev_b32_e32 v4, 16, v47
	v_and_b32_e32 v5, 0xffff0000, v47
	global_store_dword v0, v60, s[28:29]
	v_pk_fma_f32 v[2:3], v[2:3], v[46:47], v[4:5] op_sel_hi:[1,0,1]
	s_add_i32 s26, s15, s5
	s_add_i32 s5, s5, s25
	s_lshl_b32 s27, s26, 16
	s_add_u32 s28, s16, s27
	s_addc_u32 s29, s17, 0
	v_cvt_pk_bf16_f32 v60, v2, v3
	s_waitcnt vmcnt(43)
	v_lshlrev_b32_e32 v4, 16, v49
	v_and_b32_e32 v5, 0xffff0000, v49
	global_store_dword v0, v60, s[28:29]
	v_pk_fma_f32 v[2:3], v[2:3], v[48:49], v[4:5] op_sel_hi:[1,0,1]
	s_add_i32 s26, s15, s5
	s_add_i32 s5, s5, s25
	s_lshl_b32 s27, s26, 16
	s_add_u32 s28, s16, s27
	s_addc_u32 s29, s17, 0
	v_cvt_pk_bf16_f32 v60, v2, v3
	s_waitcnt vmcnt(42)
	v_lshlrev_b32_e32 v4, 16, v51
	v_and_b32_e32 v5, 0xffff0000, v51
	global_store_dword v0, v60, s[28:29]
	v_pk_fma_f32 v[2:3], v[2:3], v[50:51], v[4:5] op_sel_hi:[1,0,1]
	s_add_i32 s26, s15, s5
	s_add_i32 s5, s5, s25
	s_lshl_b32 s27, s26, 16
	s_add_u32 s28, s16, s27
	s_addc_u32 s29, s17, 0
	v_cvt_pk_bf16_f32 v60, v2, v3
	s_waitcnt vmcnt(41)
	v_lshlrev_b32_e32 v4, 16, v53
	v_and_b32_e32 v5, 0xffff0000, v53
	global_store_dword v0, v60, s[28:29]
	v_pk_fma_f32 v[2:3], v[2:3], v[52:53], v[4:5] op_sel_hi:[1,0,1]
	s_add_i32 s26, s15, s5
	s_add_i32 s5, s5, s25
	s_lshl_b32 s27, s26, 16
	s_add_u32 s28, s16, s27
	s_addc_u32 s29, s17, 0
	v_cvt_pk_bf16_f32 v60, v2, v3
	s_waitcnt vmcnt(40)
	v_lshlrev_b32_e32 v4, 16, v55
	v_and_b32_e32 v5, 0xffff0000, v55
	global_store_dword v0, v60, s[28:29]
	v_pk_fma_f32 v[2:3], v[2:3], v[54:55], v[4:5] op_sel_hi:[1,0,1]
	s_add_i32 s26, s15, s5
	s_add_i32 s5, s5, s25
	s_lshl_b32 s27, s26, 16
	s_add_u32 s28, s16, s27
	s_addc_u32 s29, s17, 0
	v_cvt_pk_bf16_f32 v60, v2, v3
	s_waitcnt vmcnt(39)
	v_lshlrev_b32_e32 v4, 16, v57
	v_and_b32_e32 v5, 0xffff0000, v57
	global_store_dword v0, v60, s[28:29]
	v_pk_fma_f32 v[2:3], v[2:3], v[56:57], v[4:5] op_sel_hi:[1,0,1]
	s_add_i32 s26, s15, s5
	s_add_i32 s5, s5, s25
	s_lshl_b32 s27, s26, 16
	s_add_u32 s28, s16, s27
	s_addc_u32 s29, s17, 0
	v_cvt_pk_bf16_f32 v60, v2, v3
	s_waitcnt vmcnt(38)
	v_lshlrev_b32_e32 v4, 16, v59
	v_and_b32_e32 v5, 0xffff0000, v59
	global_store_dword v0, v60, s[28:29]
	v_pk_fma_f32 v[2:3], v[2:3], v[58:59], v[4:5] op_sel_hi:[1,0,1]
	s_add_i32 s26, s15, s5
	s_add_i32 s5, s5, s25
	s_lshl_b32 s27, s26, 16
	s_add_u32 s28, s16, s27
	s_addc_u32 s29, s17, 0
	v_cvt_pk_bf16_f32 v60, v2, v3
	s_waitcnt vmcnt(37)
	v_lshlrev_b32_e32 v4, 16, v63
	v_and_b32_e32 v5, 0xffff0000, v63
	global_store_dword v0, v60, s[28:29]
	v_pk_fma_f32 v[2:3], v[2:3], v[62:63], v[4:5] op_sel_hi:[1,0,1]
	s_add_i32 s26, s15, s5
	s_add_i32 s5, s5, s25
	s_lshl_b32 s27, s26, 16
	s_add_u32 s28, s16, s27
	s_addc_u32 s29, s17, 0
	v_cvt_pk_bf16_f32 v60, v2, v3
	s_waitcnt vmcnt(36)
	v_lshlrev_b32_e32 v4, 16, v69
	v_and_b32_e32 v5, 0xffff0000, v69
	global_store_dword v0, v60, s[28:29]
	v_pk_fma_f32 v[2:3], v[2:3], v[68:69], v[4:5] op_sel_hi:[1,0,1]
	s_add_i32 s26, s15, s5
	s_add_i32 s5, s5, s25
	s_lshl_b32 s27, s26, 16
	s_add_u32 s28, s16, s27
	s_addc_u32 s29, s17, 0
	v_cvt_pk_bf16_f32 v60, v2, v3
	s_waitcnt vmcnt(35)
	v_lshlrev_b32_e32 v4, 16, v71
	v_and_b32_e32 v5, 0xffff0000, v71
	global_store_dword v0, v60, s[28:29]
	v_pk_fma_f32 v[2:3], v[2:3], v[70:71], v[4:5] op_sel_hi:[1,0,1]
	s_add_i32 s26, s15, s5
	s_add_i32 s5, s5, s25
	s_lshl_b32 s27, s26, 16
	s_add_u32 s28, s16, s27
	s_addc_u32 s29, s17, 0
	v_cvt_pk_bf16_f32 v60, v2, v3
	s_waitcnt vmcnt(34)
	v_lshlrev_b32_e32 v4, 16, v73
	v_and_b32_e32 v5, 0xffff0000, v73
	global_store_dword v0, v60, s[28:29]
	v_pk_fma_f32 v[2:3], v[2:3], v[72:73], v[4:5] op_sel_hi:[1,0,1]
	s_add_i32 s26, s15, s5
	s_add_i32 s5, s5, s25
	s_lshl_b32 s27, s26, 16
	s_add_u32 s28, s16, s27
	s_addc_u32 s29, s17, 0
	v_cvt_pk_bf16_f32 v60, v2, v3
	s_waitcnt vmcnt(33)
	v_lshlrev_b32_e32 v4, 16, v77
	v_and_b32_e32 v5, 0xffff0000, v77
	global_store_dword v0, v60, s[28:29]
	v_pk_fma_f32 v[2:3], v[2:3], v[76:77], v[4:5] op_sel_hi:[1,0,1]
	s_add_i32 s26, s15, s5
	s_add_i32 s5, s5, s25
	s_lshl_b32 s27, s26, 16
	s_add_u32 s28, s16, s27
	s_addc_u32 s29, s17, 0
	v_cvt_pk_bf16_f32 v60, v2, v3
	s_waitcnt vmcnt(32)
	v_lshlrev_b32_e32 v4, 16, v79
	v_and_b32_e32 v5, 0xffff0000, v79
	global_store_dword v0, v60, s[28:29]
	v_pk_fma_f32 v[2:3], v[2:3], v[78:79], v[4:5] op_sel_hi:[1,0,1]
	s_add_i32 s26, s15, s5
	s_add_i32 s5, s5, s25
	s_lshl_b32 s27, s26, 16
	s_add_u32 s28, s16, s27
	s_addc_u32 s29, s17, 0
	v_cvt_pk_bf16_f32 v60, v2, v3
	global_store_dword v0, v60, s[28:29]
	s_add_i32 s11, s11, s33
	s_add_i32 s9, s9, s10
	s_cmpk_lt_i32 s11, 0x200
	s_waitcnt vmcnt(0)
	s_cbranch_scc1 .LBB0_2137
